# select: key tiles of an item's first scoring loop shared out by wave arrival order (4/8/16-stride residue classes)
# speedup vs baseline: 1.0070x; 1.0002x over previous
; __device__ __forceinline__ void select_query(const unsigned (&u)[64], unsigned vmax, int q, int b, int lane, unsigned* MASKb) {
;     ...
;                 for (int o = 1; o < 64; o <<= 1) { const int t = __shfl_up(incl, o); if (lane >= o) incl += t; }
; __device__ __forceinline__ void select_phase(const bf16_t* Z, const bf16_t* KIb, unsigned* MASKb, unsigned* itemcnt, LAS unsigned char* lds, int wave_in, int lane_in, int bid, int G, int sub) {
;     ...
;     const int nrounds = (1024 + G - 1) / G;
;     bf16x8 qf[4][2]; u32x2 wraw;
;     ...
;     { const int r0 = nrounds - 1; int i0_ = r0 * G + ((r0 & 1) ? (G - 1 - bid) : bid); SEL_LOADQ(i0_); }
.LBB0_112:
	s_mov_b32 s100, -1
	s_abs_i32 s4, s97
	v_cvt_f32_u32_e32 v0, s4
	s_add_i32 s5, s97, 0x3ff
	s_sub_i32 s6, 0xfffffc01, s97
	s_xor_b32 s7, s5, s97
	v_rcp_iflag_f32_e32 v0, v0
	s_max_i32 s5, s5, s6
	s_sub_i32 s6, 0, s4
	s_ashr_i32 s7, s7, 31
	v_mul_f32_e32 v0, 0x4f7ffffe, v0
	v_cvt_u32_f32_e32 v0, v0
	v_and_b32_e32 v135, 15, v166
	v_readlane_b32 s38, v255, 11
	v_readlane_b32 s39, v255, 12
	v_readfirstlane_b32 s8, v0
	s_mul_i32 s6, s6, s8
	s_mul_hi_u32 s6, s8, s6
	s_add_i32 s8, s8, s6
	s_mul_hi_u32 s6, s5, s8
	s_mul_i32 s8, s6, s4
	s_sub_i32 s5, s5, s8
	s_add_i32 s9, s6, 1
	s_sub_i32 s8, s5, s4
	s_cmp_ge_u32 s5, s4
	s_cselect_b32 s6, s9, s6
	s_cselect_b32 s5, s8, s5
	s_add_i32 s8, s6, 1
	s_cmp_ge_u32 s5, s4
	s_cselect_b32 s4, s8, s6
	s_xor_b32 s4, s4, s7
	s_sub_i32 s77, s4, s7
	s_cmp_lt_i32 s77, 1
	s_cbranch_scc1 .LBB0_243
	v_readlane_b32 s4, v255, 28
	v_readlane_b32 s5, v255, 29
	s_lshl_b32 s4, s4, 10
	s_ashr_i32 s5, s4, 31
	s_lshl_b64 s[4:5], s[4:5], 2
	s_add_u32 s4, s78, s4
	s_addc_u32 s5, s79, s5
	s_add_u32 s80, s4, 0xfa08000
	s_addc_u32 s84, s5, 0
	s_not_b32 s4, s76
	s_add_i32 s86, s77, -1
	s_add_i32 s87, s97, s4
	s_bitcmp0_b32 s86, 0
	s_cselect_b32 s4, s76, s87
	s_mul_i32 s5, s86, s97
	s_add_i32 s4, s4, s5
	s_min_i32 s4, s4, 0x3ff
	s_lshl_b32 s5, s4, 12
	s_lshl_b32 s4, s4, 2
	s_and_b32 s4, s4, -16
	s_and_b32 s5, s5, 0x3000
	s_ashr_i32 s6, s4, 31
	v_ashrrev_i32_e32 v0, 1, v166
	s_add_u32 s4, s5, s4
	s_waitcnt vmcnt(2)
	v_and_b32_e32 v66, -8, v0
	v_or_b32_e32 v0, s4, v135
	v_mov_b64_e32 v[2:3], s[0:1]
	s_addc_u32 s6, 0, s6
	v_mad_u64_u32 v[34:35], s[4:5], v0, s33, v[2:3]
	v_ashrrev_i32_e32 v67, 31, v66
	v_mad_i32_i24 v35, s6, v218, v35
	v_lshl_add_u64 v[26:27], v[66:67], 1, v[34:35]
	s_mov_b64 s[4:5], 0x1000
	v_lshl_add_u64 v[28:29], v[26:27], 0, s[4:5]
	s_movk_i32 s4, 0x1000
	global_load_dwordx4 v[2:5], v[28:29], off offset:384
	global_load_dwordx4 v[6:9], v[28:29], off offset:320
	global_load_dwordx4 v[10:13], v[28:29], off offset:256
	global_load_dwordx4 v[14:17], v[28:29], off offset:192
	global_load_dwordx4 v[18:21], v[28:29], off offset:128
	global_load_dwordx4 v[22:25], v[28:29], off offset:64
	s_waitcnt vmcnt(6)
	v_add_co_u32_e32 v30, vcc, s4, v26
	v_and_b32_e32 v0, 64, v179
	s_nop 0
	v_addc_co_u32_e32 v31, vcc, 0, v27, vcc
	v_add_co_u32_e32 v34, vcc, s4, v34
	global_load_dwordx4 v[26:29], v[28:29], off offset:448
	s_nop 0
	global_load_dwordx4 v[30:33], v[30:31], off
	v_addc_co_u32_e32 v35, vcc, 0, v35, vcc
	global_load_dwordx2 v[70:71], v[34:35], off offset:1664
	v_add_u32_e32 v34, -1, v179
	v_cmp_lt_i32_e32 vcc, v34, v0
	s_mov_b32 s88, 0
	s_nop 0
	v_cndmask_b32_e32 v34, v34, v179, vcc
	v_lshlrev_b32_e32 v100, 2, v34
	v_add_u32_e32 v34, -2, v179
	v_cmp_lt_i32_e32 vcc, v34, v0
	s_nop 1
	v_cndmask_b32_e32 v34, v34, v179, vcc
	v_lshlrev_b32_e32 v101, 2, v34
	v_add_u32_e32 v34, -4, v179
	v_cmp_lt_i32_e32 vcc, v34, v0
	s_nop 1
	v_cndmask_b32_e32 v34, v34, v179, vcc
	v_lshlrev_b32_e32 v102, 2, v34
	v_add_u32_e32 v34, -8, v179
	v_cmp_lt_i32_e32 vcc, v34, v0
	s_nop 1
	v_cndmask_b32_e32 v34, v34, v179, vcc
	v_lshlrev_b32_e32 v103, 2, v34
	v_add_u32_e32 v34, -16, v179
	v_cmp_lt_i32_e32 vcc, v34, v0
	s_nop 1
	v_cndmask_b32_e32 v34, v34, v179, vcc
	v_lshlrev_b32_e32 v104, 2, v34
	v_subrev_u32_e32 v34, 32, v179
	v_cmp_lt_i32_e32 vcc, v34, v0
	s_nop 1
	v_cndmask_b32_e32 v0, v34, v179, vcc
	v_lshlrev_b32_e32 v105, 2, v0
	v_mov_b32_e32 v208, 0x24440
	ds_write_b32 v208, v1
	s_branch .LBB0_116

; __device__ __forceinline__ float bflo(unsigned w) { return __uint_as_float(w << 16); }
; __device__ __forceinline__ float bfhi(unsigned w) { return __uint_as_float(w & 0xffff0000u); }
; #define KI_LOAD(dst, i0) do { _Pragma("unroll") for (int t_ = 0; t_ < 2; ++t_) { int kt_ = ktlo + wave + 8 * ((i0) + t_); kt_ = kt_ < kthi ? kt_ : kthi - 1; \
;                 dst[t_][0] = *(const bf16x8*)(kib + (size_t)kt_ * 1024); dst[t_][1] = *(const bf16x8*)(kib + (size_t)kt_ * 1024 + 512); } } while (0)
; __device__ __forceinline__ void select_phase(const bf16_t* Z, const bf16_t* KIb, unsigned* MASKb, unsigned* itemcnt, LAS unsigned char* lds, int wave_in, int lane_in, int bid, int G, int sub) {
;     ...
;         const float w0 = bflo(wraw.x), w1 = bfhi(wraw.x), w2 = bflo(wraw.y), w3 = bfhi(wraw.y);
;         const int nkt = (q0 >> 4) + 1, nch = (nkt + 127) >> 7;
;         const bf16_t* kib = KIb + (size_t)b * 256 * 1024 + fr * 32 + fq * 8;
;         const int qa = q0 + 2 * wave, qb = qa + 1;
;         unsigned ua[64], ub[64]; unsigned vmaxa = 0u, vmaxb = 0u;
; #pragma unroll
;         for (int c = 0; c < 2; ++c) {
;             if (c < nch) {
;                 const int ktlo = 128 * c, kthi = min(nkt, ktlo + 128);
;                 bf16x8 ka[2][2], kb2[2][2];
;     ...
;                 KI_LOAD(ka, 0);
;                 for (int i0 = 0; ktlo + wave + 8 * i0 < kthi; i0 += 4) { KI_LOAD(kb2, i0 + 2); KI_COMP(ka, i0); KI_LOAD(ka, i0 + 4); KI_COMP(kb2, i0 + 2); }
.Lsf_cont:
	v_lshlrev_b32_e32 v72, 16, v70
	v_and_b32_e32 v74, 0xffff0000, v70
	v_lshlrev_b32_e32 v76, 16, v71
	v_and_b32_e32 v78, 0xffff0000, v71
	v_mov_b32_e32 v106, s75
	v_and_b32_e32 v171, -16, v68
	v_mul_lo_u32 v0, v68, s4
	s_cmp_lt_i32 s10, 1
	v_lshlrev_b32_e32 v172, 5, v68
	s_cbranch_scc1 .LBB0_128
	s_cmp_lt_i32 s100, 0
	s_cbranch_scc1 .Lrk_even
	v_mov_b32_e32 v208, 0x24440
	v_mov_b32_e32 v209, 1
	s_mov_b64 vcc, exec
	s_mov_b64 exec, 1
	ds_add_rtn_u32 v208, v208, v209
	s_mov_b64 exec, vcc
	s_waitcnt lgkmcnt(0)
	v_readfirstlane_b32 s26, v208
	s_and_b32 s26, s26, 7
	s_lshl_b32 s27, s26, 2
	s_add_i32 s28, s27, -6
	s_add_i32 s29, s27, -13
	s_cmp_lt_u32 s26, 4
	s_cselect_b32 s29, s28, s29
	s_cselect_b32 s27, 8, 16
	s_cmp_lt_u32 s26, 2
	s_cselect_b32 s29, s26, s29
	s_cselect_b32 s27, 4, s27
	s_branch .Lrk_set
.Lrk_even:
	s_mov_b32 s29, s6
	s_mov_b32 s27, 8
.Lrk_set:
	v_mov_b32_e32 v208, s29
	v_mov_b32_e32 v209, 0
	v_mov_b32_e32 v203, s27
	v_lshlrev_b32_e32 v204, 1, v203
	v_lshlrev_b32_e32 v206, 2, v203
	v_add_u32_e32 v205, v204, v203
	v_add_u32_e32 v207, v206, v203
	s_min_i32 s11, s8, 0x7f
	v_cmp_ge_i32_e32 vcc, s11, v208
	s_and_saveexec_b64 s[4:5], vcc
	s_cbranch_execz .LBB0_121
	v_add_u32_e32 v34, v203, v208
	v_min_i32_e32 v34, s11, v34
	v_ashrrev_i32_e32 v35, 31, v34
	v_ashrrev_i32_e64 v87, 31, s6
	v_lshlrev_b64 v[34:35], 11, v[34:35]
	v_lshlrev_b64 v[42:43], 11, v[208:209]
	v_lshl_add_u64 v[38:39], v[80:81], 0, v[34:35]
	v_lshl_add_u64 v[46:47], v[80:81], 0, v[42:43]
	global_load_dwordx4 v[34:37], v[38:39], off offset:1024
	s_nop 0
	global_load_dwordx4 v[38:41], v[38:39], off
	s_nop 0
	global_load_dwordx4 v[42:45], v[46:47], off offset:1024
	s_nop 0
	global_load_dwordx4 v[46:49], v[46:47], off
	v_mov_b32_e32 v79, v78
	v_mov_b32_e32 v88, v78
	v_mov_b32_e32 v89, v78
	v_mov_b32_e32 v77, v76
	v_mov_b32_e32 v90, v76
	v_mov_b32_e32 v91, v76
	v_mov_b32_e32 v75, v74
	v_mov_b32_e32 v92, v74
	v_mov_b32_e32 v93, v74
	v_mov_b32_e32 v73, v72
	v_mov_b32_e32 v94, v72
	v_mov_b32_e32 v95, v72
	s_mov_b64 s[6:7], 0
	v_mov_b32_e32 v87, v208
.LBB0_120:
	s_waitcnt vmcnt(0)
	v_mfma_f32_16x16x32_bf16 v[108:111], v[46:49], v[30:33], 0
	v_add_u32_e32 v50, v204, v87
	v_min_i32_e32 v98, s11, v50
	v_ashrrev_i32_e32 v99, 31, v98
	v_mfma_f32_16x16x32_bf16 v[112:115], v[46:49], v[18:21], 0
	v_lshlrev_b64 v[50:51], 11, v[98:99]
	v_lshl_add_u64 v[50:51], v[80:81], 0, v[50:51]
	global_load_dwordx4 v[58:61], v[50:51], off
	global_load_dwordx4 v[62:65], v[50:51], off offset:1024
	v_mfma_f32_16x16x32_bf16 v[116:119], v[46:49], v[10:13], 0
	v_add_u32_e32 v50, v205, v87
	v_min_i32_e32 v96, s11, v50
	v_ashrrev_i32_e32 v97, 31, v96
	v_mfma_f32_16x16x32_bf16 v[46:49], v[46:49], v[2:5], 0
	v_lshlrev_b64 v[50:51], 11, v[96:97]
	v_min_i32_e32 v97, s11, v87
	v_lshl_add_u64 v[54:55], v[80:81], 0, v[50:51]
	v_mfma_f32_16x16x32_bf16 v[108:111], v[42:45], v[22:25], v[108:111]
	global_load_dwordx4 v[50:53], v[54:55], off
	s_nop 0
	global_load_dwordx4 v[54:57], v[54:55], off offset:1024
	v_mfma_f32_16x16x32_bf16 v[112:115], v[42:45], v[14:17], v[112:115]
	s_nop 3
	v_max_i32_e32 v111, 0, v111
	v_max_i32_e32 v110, 0, v110
	v_pk_fma_f32 v[110:111], v[110:111], v[94:95], 0 op_sel_hi:[1,1,0]
	v_mfma_f32_16x16x32_bf16 v[116:119], v[42:45], v[6:9], v[116:119]
	v_max_i32_e32 v109, 0, v109
	v_max_i32_e32 v115, 0, v115
	v_max_i32_e32 v114, 0, v114
	v_mfma_f32_16x16x32_bf16 v[42:45], v[42:45], v[26:29], v[46:49]
	v_max_i32_e32 v108, 0, v108
	v_pk_fma_f32 v[110:111], v[114:115], v[92:93], v[110:111]
	v_max_i32_e32 v113, 0, v113
	s_nop 0
	v_max_i32_e32 v47, 0, v119
	v_max_i32_e32 v46, 0, v118
	s_nop 1
	v_max_i32_e32 v45, 0, v45
	v_max_i32_e32 v44, 0, v44
	v_max_i32_e32 v112, 0, v112
	v_pk_fma_f32 v[108:109], v[108:109], v[72:73], 0 op_sel_hi:[1,1,0]
	v_pk_fma_f32 v[46:47], v[46:47], v[90:91], v[110:111]
	v_max_i32_e32 v49, 0, v117
	v_max_i32_e32 v48, 0, v116
	v_pk_fma_f32 v[108:109], v[112:113], v[74:75], v[108:109]
	v_pk_fma_f32 v[44:45], v[44:45], v[88:89], v[46:47]
	v_lshlrev_b32_e32 v47, 3, v97
	v_max_i32_e32 v43, 0, v43
	v_max_i32_e32 v42, 0, v42
	v_pk_fma_f32 v[48:49], v[48:49], v[76:77], v[108:109]
	v_lshl_add_u32 v46, v97, 6, v69
	v_and_b32_e32 v47, -16, v47
	v_pk_fma_f32 v[42:43], v[42:43], v[78:79], v[48:49]
	v_add3_u32 v46, v46, v47, v171
	ds_write_b128 v46, v[42:45]
	v_add_u32_e32 v42, v203, v87
	v_min_i32_e32 v97, s11, v42
	v_mfma_f32_16x16x32_bf16 v[42:45], v[38:41], v[30:33], 0
	v_mfma_f32_16x16x32_bf16 v[46:49], v[38:41], v[18:21], 0
	v_mfma_f32_16x16x32_bf16 v[108:111], v[38:41], v[10:13], 0
	v_mfma_f32_16x16x32_bf16 v[38:41], v[38:41], v[2:5], 0
	v_mfma_f32_16x16x32_bf16 v[42:45], v[34:37], v[22:25], v[42:45]
	v_mfma_f32_16x16x32_bf16 v[46:49], v[34:37], v[14:17], v[46:49]
	v_mfma_f32_16x16x32_bf16 v[108:111], v[34:37], v[6:9], v[108:111]
	s_nop 5
	v_max_i32_e32 v45, 0, v45
	v_max_i32_e32 v44, 0, v44
	v_max_i32_e32 v49, 0, v49
	v_mfma_f32_16x16x32_bf16 v[34:37], v[34:37], v[26:29], v[38:41]
	v_max_i32_e32 v48, 0, v48
	v_pk_fma_f32 v[44:45], v[44:45], v[94:95], 0 op_sel_hi:[1,1,0]
	v_max_i32_e32 v43, 0, v43
	v_max_i32_e32 v39, 0, v111
	v_max_i32_e32 v38, 0, v110
	v_max_i32_e32 v42, 0, v42
	v_pk_fma_f32 v[44:45], v[48:49], v[92:93], v[44:45]
	s_nop 0
	v_max_i32_e32 v37, 0, v37
	v_max_i32_e32 v36, 0, v36
	v_max_i32_e32 v47, 0, v47
	v_max_i32_e32 v46, 0, v46
	v_pk_fma_f32 v[42:43], v[42:43], v[72:73], 0 op_sel_hi:[1,1,0]
	v_pk_fma_f32 v[38:39], v[38:39], v[90:91], v[44:45]
	v_max_i32_e32 v41, 0, v109
	v_max_i32_e32 v40, 0, v108
	v_pk_fma_f32 v[42:43], v[46:47], v[74:75], v[42:43]
	v_pk_fma_f32 v[36:37], v[36:37], v[88:89], v[38:39]
	v_lshlrev_b32_e32 v39, 3, v97
	v_max_i32_e32 v35, 0, v35
	v_max_i32_e32 v34, 0, v34
	v_pk_fma_f32 v[40:41], v[40:41], v[76:77], v[42:43]
	v_lshl_add_u32 v38, v97, 6, v69
	v_and_b32_e32 v39, -16, v39
	v_pk_fma_f32 v[34:35], v[34:35], v[78:79], v[40:41]
	v_add3_u32 v38, v38, v39, v171
	v_add_u32_e32 v97, v206, v87
	ds_write_b128 v38, v[34:37]
	v_min_i32_e32 v34, s11, v97
	v_ashrrev_i32_e32 v35, 31, v34
	v_lshlrev_b64 v[34:35], 11, v[34:35]
	v_lshl_add_u64 v[34:35], v[80:81], 0, v[34:35]
	global_load_dwordx4 v[46:49], v[34:35], off
	global_load_dwordx4 v[42:45], v[34:35], off offset:1024
	v_add_u32_e32 v34, v207, v87
	v_min_i32_e32 v34, s11, v34
	v_ashrrev_i32_e32 v35, 31, v34
	v_lshlrev_b64 v[34:35], 11, v[34:35]
	v_lshl_add_u64 v[34:35], v[80:81], 0, v[34:35]
	global_load_dwordx4 v[38:41], v[34:35], off
	s_nop 0
	global_load_dwordx4 v[34:37], v[34:35], off offset:1024
	s_waitcnt vmcnt(7)
; #define KI_LOAD(dst, i0) do { _Pragma("unroll") for (int t_ = 0; t_ < 2; ++t_) { int kt_ = ktlo + wave + 8 * ((i0) + t_); kt_ = kt_ < kthi ? kt_ : kthi - 1; \
;                 dst[t_][0] = *(const bf16x8*)(kib + (size_t)kt_ * 1024); dst[t_][1] = *(const bf16x8*)(kib + (size_t)kt_ * 1024 + 512); } } while (0)
; __device__ __forceinline__ void select_phase(const bf16_t* Z, const bf16_t* KIb, unsigned* MASKb, unsigned* itemcnt, LAS unsigned char* lds, int wave_in, int lane_in, int bid, int G, int sub) {
;     ...
;                 KI_LOAD(ka, 0);
;                 for (int i0 = 0; ktlo + wave + 8 * i0 < kthi; i0 += 4) { KI_LOAD(kb2, i0 + 2); KI_COMP(ka, i0); KI_LOAD(ka, i0 + 4); KI_COMP(kb2, i0 + 2); }
	v_mfma_f32_16x16x32_bf16 v[108:111], v[58:61], v[30:33], 0
	v_cmp_lt_i32_e32 vcc, s11, v97
	s_or_b64 s[6:7], vcc, s[6:7]
	v_mov_b32_e32 v87, v97
	v_mfma_f32_16x16x32_bf16 v[112:115], v[58:61], v[18:21], 0
	v_mfma_f32_16x16x32_bf16 v[116:119], v[58:61], v[10:13], 0
	v_mfma_f32_16x16x32_bf16 v[58:61], v[58:61], v[2:5], 0
	s_waitcnt vmcnt(6)
	v_mfma_f32_16x16x32_bf16 v[108:111], v[62:65], v[22:25], v[108:111]
	v_mfma_f32_16x16x32_bf16 v[112:115], v[62:65], v[14:17], v[112:115]
	v_mfma_f32_16x16x32_bf16 v[116:119], v[62:65], v[6:9], v[116:119]
	s_nop 5
	v_max_i32_e32 v111, 0, v111
	v_max_i32_e32 v110, 0, v110
	v_max_i32_e32 v115, 0, v115
	v_mfma_f32_16x16x32_bf16 v[58:61], v[62:65], v[26:29], v[58:61]
	v_max_i32_e32 v114, 0, v114
	v_pk_fma_f32 v[110:111], v[110:111], v[94:95], 0 op_sel_hi:[1,1,0]
	v_max_i32_e32 v63, 0, v119
	v_max_i32_e32 v62, 0, v118
	v_max_i32_e32 v109, 0, v109
	v_max_i32_e32 v108, 0, v108
	v_pk_fma_f32 v[110:111], v[114:115], v[92:93], v[110:111]
	s_nop 0
	v_max_i32_e32 v61, 0, v61
	v_max_i32_e32 v60, 0, v60
	v_max_i32_e32 v113, 0, v113
	v_max_i32_e32 v112, 0, v112
	v_pk_fma_f32 v[108:109], v[108:109], v[72:73], 0 op_sel_hi:[1,1,0]
	v_pk_fma_f32 v[62:63], v[62:63], v[90:91], v[110:111]
	v_max_i32_e32 v65, 0, v117
	v_max_i32_e32 v64, 0, v116
	v_pk_fma_f32 v[108:109], v[112:113], v[74:75], v[108:109]
	v_pk_fma_f32 v[60:61], v[60:61], v[88:89], v[62:63]
	v_lshlrev_b32_e32 v63, 3, v98
	v_max_i32_e32 v59, 0, v59
	v_max_i32_e32 v58, 0, v58
	v_pk_fma_f32 v[64:65], v[64:65], v[76:77], v[108:109]
	v_lshl_add_u32 v62, v98, 6, v69
	v_and_b32_e32 v63, -16, v63
	v_pk_fma_f32 v[58:59], v[58:59], v[78:79], v[64:65]
	v_add3_u32 v62, v62, v63, v171
	ds_write_b128 v62, v[58:61]
	s_waitcnt vmcnt(5)
	v_mfma_f32_16x16x32_bf16 v[58:61], v[50:53], v[30:33], 0
	v_mfma_f32_16x16x32_bf16 v[62:65], v[50:53], v[18:21], 0
	v_mfma_f32_16x16x32_bf16 v[108:111], v[50:53], v[10:13], 0
	v_mfma_f32_16x16x32_bf16 v[50:53], v[50:53], v[2:5], 0
	s_waitcnt vmcnt(4)
	v_mfma_f32_16x16x32_bf16 v[58:61], v[54:57], v[22:25], v[58:61]
	v_mfma_f32_16x16x32_bf16 v[62:65], v[54:57], v[14:17], v[62:65]
	v_mfma_f32_16x16x32_bf16 v[108:111], v[54:57], v[6:9], v[108:111]
	s_nop 5
	v_max_i32_e32 v61, 0, v61
	v_max_i32_e32 v60, 0, v60
	v_max_i32_e32 v65, 0, v65
	v_mfma_f32_16x16x32_bf16 v[50:53], v[54:57], v[26:29], v[50:53]
	v_max_i32_e32 v64, 0, v64
	v_pk_fma_f32 v[60:61], v[60:61], v[94:95], 0 op_sel_hi:[1,1,0]
	v_max_i32_e32 v55, 0, v111
	v_max_i32_e32 v54, 0, v110
	v_max_i32_e32 v59, 0, v59
	v_max_i32_e32 v58, 0, v58
	v_pk_fma_f32 v[60:61], v[64:65], v[92:93], v[60:61]
	s_nop 0
	v_max_i32_e32 v53, 0, v53
	v_max_i32_e32 v52, 0, v52
	v_max_i32_e32 v63, 0, v63
	v_max_i32_e32 v62, 0, v62
	v_pk_fma_f32 v[58:59], v[58:59], v[72:73], 0 op_sel_hi:[1,1,0]
	v_pk_fma_f32 v[54:55], v[54:55], v[90:91], v[60:61]
	v_max_i32_e32 v57, 0, v109
	v_max_i32_e32 v56, 0, v108
	v_pk_fma_f32 v[58:59], v[62:63], v[74:75], v[58:59]
	v_pk_fma_f32 v[52:53], v[52:53], v[88:89], v[54:55]
	v_lshlrev_b32_e32 v55, 3, v96
	v_max_i32_e32 v51, 0, v51
	v_max_i32_e32 v50, 0, v50
	v_pk_fma_f32 v[56:57], v[56:57], v[76:77], v[58:59]
	v_lshl_add_u32 v54, v96, 6, v69
	v_and_b32_e32 v55, -16, v55
	v_pk_fma_f32 v[50:51], v[50:51], v[78:79], v[56:57]
	v_add3_u32 v54, v54, v55, v171
	ds_write_b128 v54, v[50:53]
	s_andn2_b64 exec, exec, s[6:7]
	s_cbranch_execnz .LBB0_120
